# stack2 + halo mini-GEMM: hoisted prefetch, fragment reads ahead of the staging writes, counted lgkmcnt so MFMAs do not wait for the writes
# speedup vs baseline: 1.0022x; 1.0022x over previous
; #define LAS __attribute__((address_space(3)))
; __device__ __forceinline__ void halo_gemm_unit(int unit, int tid, int lane, int wave, LAS unsigned char* lds, const bf16_t* __restrict__ XBp, const bf16_t* __restrict__ Wup, bf16_t* __restrict__ HALOp) {
;     ...
;     for (int c = 0; c < 16; c += 2) {
;         { const int k2 = (c + 2 < 16) ? 64 * (c + 2) : 0;
; #pragma unroll
;           for (int i = 0; i < 2; ++i) ra0[i] = *(const v4u*)(gA[i] + k2);
; #pragma unroll
;           for (int i = 0; i < 4; ++i) rb0[i] = *(const v4u*)(gB[i] + k2);
;           HG_COMPUTE(lds);
; #pragma unroll
;           for (int i = 0; i < 2; ++i) *(LAS v4u*)(lds + HG_STAGE + lA[i]) = ra1[i];
; #pragma unroll
;           for (int i = 0; i < 4; ++i) *(LAS v4u*)(lds + HG_STAGE + lB[i]) = rb1[i];
;           __syncthreads(); }
;         { const int k3 = (c + 3 < 16) ? 64 * (c + 3) : 0;
; #pragma unroll
;           for (int i = 0; i < 2; ++i) ra1[i] = *(const v4u*)(gA[i] + k3);
; #pragma unroll
;           for (int i = 0; i < 4; ++i) rb1[i] = *(const v4u*)(gB[i] + k3);
;           HG_COMPUTE(lds + HG_STAGE);
;           if (c + 2 < 16) {
; #pragma unroll
;               for (int i = 0; i < 2; ++i) *(LAS v4u*)(lds + lA[i]) = ra0[i];
; #pragma unroll
;               for (int i = 0; i < 4; ++i) *(LAS v4u*)(lds + lB[i]) = rb0[i];
;           }
;           __syncthreads(); }
;     }
.LBB0_684:
	s_cmp_gt_u32 s12, 13
	s_cselect_b64 s[8:9], -1, 0
	s_sub_i32 s0, s10, 64
	s_cmp_lt_u32 s12, 14
	s_cselect_b32 s6, s0, 0
	s_lshl_b64 s[0:1], s[6:7], 1
	s_cmp_lt_u32 s12, 13
	s_cselect_b32 s6, s10, 0
	v_lshl_add_u64 v[110:111], v[124:125], 0, s[0:1]
	v_lshl_add_u64 v[90:91], v[114:115], 0, s[0:1]
	v_lshl_add_u64 v[94:95], v[116:117], 0, s[0:1]
	v_lshl_add_u64 v[106:107], v[122:123], 0, s[0:1]
	v_lshl_add_u64 v[98:99], v[118:119], 0, s[0:1]
	v_lshl_add_u64 v[102:103], v[120:121], 0, s[0:1]
	global_load_dwordx4 v[90:93], v[90:91], off
	s_nop 0
	global_load_dwordx4 v[94:97], v[94:95], off
	s_nop 0
	global_load_dwordx4 v[98:101], v[98:99], off
	s_nop 0
	global_load_dwordx4 v[102:105], v[102:103], off
	s_nop 0
	global_load_dwordx4 v[106:109], v[106:107], off
	s_nop 0
	global_load_dwordx4 v[110:113], v[110:111], off
	s_nop 0
	v_add_u32_e32 v139, 0, v132
	ds_read_b128 v[156:159], v139 offset:18432
	ds_read_b128 v[160:163], v133
	ds_read_b128 v[164:167], v133 offset:32
	ds_read_b128 v[168:171], v139 offset:18464
	ds_read_b128 v[172:175], v139 offset:23040
	ds_read_b128 v[176:179], v139 offset:23072
	s_waitcnt lgkmcnt(4)
	v_mfma_f32_32x32x16_bf16 v[50:65], v[156:159], v[160:163], v[50:65]
	s_waitcnt lgkmcnt(1)
	v_mfma_f32_32x32x16_bf16 v[34:49], v[172:175], v[160:163], v[34:49]
	ds_read_b128 v[160:163], v133 offset:4608
	ds_read_b128 v[140:143], v133 offset:4640
	s_and_b64 vcc, exec, s[8:9]
	s_waitcnt lgkmcnt(1)
	v_mfma_f32_32x32x16_bf16 v[18:33], v[156:159], v[160:163], v[18:33]
	v_mfma_f32_32x32x16_bf16 v[2:17], v[172:175], v[160:163], v[2:17]
	v_mfma_f32_32x32x16_bf16 v[50:65], v[168:171], v[164:167], v[50:65]
	v_mfma_f32_32x32x16_bf16 v[34:49], v[176:179], v[164:167], v[34:49]
	s_waitcnt lgkmcnt(0)
	v_mfma_f32_32x32x16_bf16 v[18:33], v[168:171], v[140:143], v[18:33]
	ds_read_b128 v[156:159], v139 offset:18496
	ds_read_b128 v[160:163], v133 offset:64
	ds_read_b128 v[164:167], v133 offset:96
	ds_read_b128 v[168:171], v139 offset:18528
	v_mfma_f32_32x32x16_bf16 v[2:17], v[176:179], v[140:143], v[2:17]
	ds_read_b128 v[172:175], v139 offset:23104
	ds_read_b128 v[140:143], v139 offset:23136
	ds_read_b128 v[204:207], v133 offset:4672
	ds_read_b128 v[146:149], v133 offset:4704
	s_waitcnt vmcnt(11)
	ds_write_b128 v128, v[66:69] offset:55296
	s_waitcnt vmcnt(10)
	ds_write_b128 v129, v[70:73] offset:55296
	s_waitcnt vmcnt(9)
	ds_write_b128 v134, v[74:77] offset:55296
	s_waitcnt vmcnt(8)
	ds_write_b128 v135, v[78:81] offset:55296
	s_waitcnt vmcnt(6)
	ds_write_b128 v136, v[86:89] offset:55296
	ds_write_b128 v137, v[82:85] offset:55296
	s_waitcnt lgkmcnt(12)
	v_mfma_f32_32x32x16_bf16 v[50:65], v[156:159], v[160:163], v[50:65]
	s_waitcnt lgkmcnt(9)
	v_mfma_f32_32x32x16_bf16 v[34:49], v[172:175], v[160:163], v[34:49]
	s_waitcnt lgkmcnt(7)
	v_mfma_f32_32x32x16_bf16 v[18:33], v[156:159], v[204:207], v[18:33]
	v_mfma_f32_32x32x16_bf16 v[2:17], v[172:175], v[204:207], v[2:17]
	v_mfma_f32_32x32x16_bf16 v[50:65], v[168:171], v[164:167], v[50:65]
	v_mfma_f32_32x32x16_bf16 v[34:49], v[140:143], v[164:167], v[34:49]
	s_waitcnt lgkmcnt(6)
	v_mfma_f32_32x32x16_bf16 v[18:33], v[168:171], v[146:149], v[18:33]
	s_waitcnt lgkmcnt(0)
	s_barrier
	s_lshl_b64 s[0:1], s[6:7], 1
	v_lshl_add_u64 v[150:151], v[124:125], 0, s[0:1]
	v_lshl_add_u64 v[86:87], v[122:123], 0, s[0:1]
	v_lshl_add_u64 v[66:67], v[114:115], 0, s[0:1]
	v_lshl_add_u64 v[70:71], v[116:117], 0, s[0:1]
	v_lshl_add_u64 v[78:79], v[120:121], 0, s[0:1]
	v_lshl_add_u64 v[74:75], v[118:119], 0, s[0:1]
	global_load_dwordx4 v[66:69], v[66:67], off
	s_nop 0
	global_load_dwordx4 v[70:73], v[70:71], off
	s_nop 0
	global_load_dwordx4 v[74:77], v[74:75], off
	s_nop 0
	global_load_dwordx4 v[78:81], v[78:79], off
	s_nop 0
	global_load_dwordx4 v[86:89], v[86:87], off
	s_nop 0
	global_load_dwordx4 v[82:85], v[150:151], off
	s_nop 0
	v_mfma_f32_32x32x16_bf16 v[2:17], v[140:143], v[146:149], v[2:17]
	ds_read_b128 v[180:183], v138 offset:55296
	ds_read_b128 v[184:187], v133 offset:55296
	ds_read_b128 v[188:191], v133 offset:55328
	ds_read_b128 v[192:195], v138 offset:55328
	ds_read_b128 v[196:199], v138 offset:59904
	ds_read_b128 v[200:203], v138 offset:59936
	s_waitcnt lgkmcnt(4)
	v_mfma_f32_32x32x16_bf16 v[50:65], v[180:183], v[184:187], v[50:65]
	s_waitcnt lgkmcnt(1)
	v_mfma_f32_32x32x16_bf16 v[34:49], v[196:199], v[184:187], v[34:49]
	ds_read_b128 v[184:187], v133 offset:59904
	ds_read_b128 v[140:143], v133 offset:59936
	s_waitcnt lgkmcnt(1)
	v_mfma_f32_32x32x16_bf16 v[18:33], v[180:183], v[184:187], v[18:33]
	v_mfma_f32_32x32x16_bf16 v[2:17], v[196:199], v[184:187], v[2:17]
	v_mfma_f32_32x32x16_bf16 v[50:65], v[192:195], v[188:191], v[50:65]
	v_mfma_f32_32x32x16_bf16 v[34:49], v[200:203], v[188:191], v[34:49]
	ds_read_b128 v[180:183], v138 offset:55360
	ds_read_b128 v[184:187], v133 offset:55360
	ds_read_b128 v[188:191], v133 offset:55392
	ds_read_b128 v[196:199], v138 offset:55392
	s_waitcnt lgkmcnt(4)
	v_mfma_f32_32x32x16_bf16 v[18:33], v[192:195], v[140:143], v[18:33]
	v_mfma_f32_32x32x16_bf16 v[2:17], v[200:203], v[140:143], v[2:17]
	ds_read_b128 v[192:195], v138 offset:59968
	ds_read_b128 v[140:143], v138 offset:60000
	ds_read_b128 v[208:211], v133 offset:59968
	ds_read_b128 v[146:149], v133 offset:60000
	s_waitcnt vmcnt(11)
	ds_write_b128 v128, v[90:93]
	s_waitcnt vmcnt(10)
	ds_write_b128 v129, v[94:97]
	s_waitcnt vmcnt(9)
	ds_write_b128 v128, v[98:101] offset:18432
	s_waitcnt vmcnt(8)
	ds_write_b128 v129, v[102:105] offset:18432
	s_waitcnt vmcnt(7)
	ds_write_b128 v130, v[106:109] offset:18432
	s_waitcnt vmcnt(6)
	ds_write_b128 v131, v[110:113] offset:18432
	s_waitcnt lgkmcnt(12)
	v_mfma_f32_32x32x16_bf16 v[50:65], v[180:183], v[184:187], v[50:65]
	s_waitcnt lgkmcnt(9)
	v_mfma_f32_32x32x16_bf16 v[34:49], v[192:195], v[184:187], v[34:49]
	s_waitcnt lgkmcnt(7)
	v_mfma_f32_32x32x16_bf16 v[18:33], v[180:183], v[208:211], v[18:33]
	v_mfma_f32_32x32x16_bf16 v[2:17], v[192:195], v[208:211], v[2:17]
	v_mfma_f32_32x32x16_bf16 v[50:65], v[196:199], v[188:191], v[50:65]
	v_mfma_f32_32x32x16_bf16 v[34:49], v[140:143], v[188:191], v[34:49]
	s_waitcnt lgkmcnt(6)
	v_mfma_f32_32x32x16_bf16 v[18:33], v[196:199], v[146:149], v[18:33]
	v_mfma_f32_32x32x16_bf16 v[2:17], v[140:143], v[146:149], v[2:17]
	s_branch .LBB0_683

; #define LAS __attribute__((address_space(3)))
; __device__ __forceinline__ void halo_gemm_unit(int unit, int tid, int lane, int wave, LAS unsigned char* lds, const bf16_t* __restrict__ XBp, const bf16_t* __restrict__ Wup, bf16_t* __restrict__ HALOp) {
;     ...
;     for (int c = 0; c < 16; c += 2) {
;         { const int k2 = (c + 2 < 16) ? 64 * (c + 2) : 0;
; #pragma unroll
;           for (int i = 0; i < 2; ++i) ra0[i] = *(const v4u*)(gA[i] + k2);
; #pragma unroll
;           for (int i = 0; i < 4; ++i) rb0[i] = *(const v4u*)(gB[i] + k2);
;           HG_COMPUTE(lds);
; #pragma unroll
;           for (int i = 0; i < 2; ++i) *(LAS v4u*)(lds + HG_STAGE + lA[i]) = ra1[i];
; #pragma unroll
;           for (int i = 0; i < 4; ++i) *(LAS v4u*)(lds + HG_STAGE + lB[i]) = rb1[i];
;           __syncthreads(); }
;         { const int k3 = (c + 3 < 16) ? 64 * (c + 3) : 0;
; #pragma unroll
;           for (int i = 0; i < 2; ++i) ra1[i] = *(const v4u*)(gA[i] + k3);
; #pragma unroll
;           for (int i = 0; i < 4; ++i) rb1[i] = *(const v4u*)(gB[i] + k3);
;           HG_COMPUTE(lds + HG_STAGE);
;           if (c + 2 < 16) {
; #pragma unroll
;               for (int i = 0; i < 2; ++i) *(LAS v4u*)(lds + lA[i]) = ra0[i];
; #pragma unroll
;               for (int i = 0; i < 4; ++i) *(LAS v4u*)(lds + lB[i]) = rb0[i];
;           }
;           __syncthreads(); }
;     }
.LBB0_1756:
	s_cmp_gt_u32 s14, 13
	s_cselect_b64 s[10:11], -1, 0
	s_sub_i32 s0, s12, 64
	s_cmp_lt_u32 s14, 14
	s_cselect_b32 s8, s0, 0
	s_lshl_b64 s[0:1], s[8:9], 1
	s_cmp_lt_u32 s14, 13
	s_cselect_b32 s8, s12, 0
	v_lshl_add_u64 v[110:111], v[124:125], 0, s[0:1]
	v_lshl_add_u64 v[90:91], v[114:115], 0, s[0:1]
	v_lshl_add_u64 v[94:95], v[116:117], 0, s[0:1]
	v_lshl_add_u64 v[106:107], v[122:123], 0, s[0:1]
	v_lshl_add_u64 v[98:99], v[118:119], 0, s[0:1]
	v_lshl_add_u64 v[102:103], v[120:121], 0, s[0:1]
	global_load_dwordx4 v[90:93], v[90:91], off
	s_nop 0
	global_load_dwordx4 v[94:97], v[94:95], off
	s_nop 0
	global_load_dwordx4 v[98:101], v[98:99], off
	s_nop 0
	global_load_dwordx4 v[102:105], v[102:103], off
	s_nop 0
	global_load_dwordx4 v[106:109], v[106:107], off
	s_nop 0
	global_load_dwordx4 v[110:113], v[110:111], off
	s_nop 0
	v_add_u32_e32 v139, 0, v132
	ds_read_b128 v[156:159], v139 offset:18432
	ds_read_b128 v[160:163], v133
	ds_read_b128 v[164:167], v133 offset:32
	ds_read_b128 v[168:171], v139 offset:18464
	ds_read_b128 v[172:175], v139 offset:23040
	ds_read_b128 v[176:179], v139 offset:23072
	s_waitcnt lgkmcnt(4)
	v_mfma_f32_32x32x16_bf16 v[50:65], v[156:159], v[160:163], v[50:65]
	s_waitcnt lgkmcnt(1)
	v_mfma_f32_32x32x16_bf16 v[34:49], v[172:175], v[160:163], v[34:49]
	ds_read_b128 v[160:163], v133 offset:4608
	ds_read_b128 v[140:143], v133 offset:4640
	s_and_b64 vcc, exec, s[10:11]
	s_waitcnt lgkmcnt(1)
	v_mfma_f32_32x32x16_bf16 v[18:33], v[156:159], v[160:163], v[18:33]
	v_mfma_f32_32x32x16_bf16 v[2:17], v[172:175], v[160:163], v[2:17]
	v_mfma_f32_32x32x16_bf16 v[50:65], v[168:171], v[164:167], v[50:65]
	v_mfma_f32_32x32x16_bf16 v[34:49], v[176:179], v[164:167], v[34:49]
	s_waitcnt lgkmcnt(0)
	v_mfma_f32_32x32x16_bf16 v[18:33], v[168:171], v[140:143], v[18:33]
	ds_read_b128 v[156:159], v139 offset:18496
	ds_read_b128 v[160:163], v133 offset:64
	ds_read_b128 v[164:167], v133 offset:96
	ds_read_b128 v[168:171], v139 offset:18528
	v_mfma_f32_32x32x16_bf16 v[2:17], v[176:179], v[140:143], v[2:17]
	ds_read_b128 v[172:175], v139 offset:23104
	ds_read_b128 v[140:143], v139 offset:23136
	ds_read_b128 v[204:207], v133 offset:4672
	ds_read_b128 v[144:147], v133 offset:4704
	s_waitcnt vmcnt(11)
	ds_write_b128 v128, v[66:69] offset:55296
	s_waitcnt vmcnt(10)
	ds_write_b128 v129, v[70:73] offset:55296
	s_waitcnt vmcnt(9)
	ds_write_b128 v134, v[74:77] offset:55296
	s_waitcnt vmcnt(8)
	ds_write_b128 v135, v[78:81] offset:55296
	s_waitcnt vmcnt(6)
	ds_write_b128 v136, v[86:89] offset:55296
	ds_write_b128 v137, v[82:85] offset:55296
	s_waitcnt lgkmcnt(12)
	v_mfma_f32_32x32x16_bf16 v[50:65], v[156:159], v[160:163], v[50:65]
	s_waitcnt lgkmcnt(9)
	v_mfma_f32_32x32x16_bf16 v[34:49], v[172:175], v[160:163], v[34:49]
	s_waitcnt lgkmcnt(7)
	v_mfma_f32_32x32x16_bf16 v[18:33], v[156:159], v[204:207], v[18:33]
	v_mfma_f32_32x32x16_bf16 v[2:17], v[172:175], v[204:207], v[2:17]
	v_mfma_f32_32x32x16_bf16 v[50:65], v[168:171], v[164:167], v[50:65]
	v_mfma_f32_32x32x16_bf16 v[34:49], v[140:143], v[164:167], v[34:49]
	s_waitcnt lgkmcnt(6)
	v_mfma_f32_32x32x16_bf16 v[18:33], v[168:171], v[144:147], v[18:33]
	s_waitcnt lgkmcnt(0)
	s_barrier
	s_lshl_b64 s[0:1], s[8:9], 1
	v_lshl_add_u64 v[148:149], v[124:125], 0, s[0:1]
	v_lshl_add_u64 v[86:87], v[122:123], 0, s[0:1]
	v_lshl_add_u64 v[66:67], v[114:115], 0, s[0:1]
	v_lshl_add_u64 v[70:71], v[116:117], 0, s[0:1]
	v_lshl_add_u64 v[78:79], v[120:121], 0, s[0:1]
	v_lshl_add_u64 v[74:75], v[118:119], 0, s[0:1]
	global_load_dwordx4 v[66:69], v[66:67], off
	s_nop 0
	global_load_dwordx4 v[70:73], v[70:71], off
	s_nop 0
	global_load_dwordx4 v[74:77], v[74:75], off
	s_nop 0
	global_load_dwordx4 v[78:81], v[78:79], off
	s_nop 0
	global_load_dwordx4 v[86:89], v[86:87], off
	s_nop 0
	global_load_dwordx4 v[82:85], v[148:149], off
	s_nop 0
	v_mfma_f32_32x32x16_bf16 v[2:17], v[140:143], v[144:147], v[2:17]
	ds_read_b128 v[180:183], v138 offset:55296
	ds_read_b128 v[184:187], v133 offset:55296
	ds_read_b128 v[188:191], v133 offset:55328
	ds_read_b128 v[192:195], v138 offset:55328
	ds_read_b128 v[196:199], v138 offset:59904
	ds_read_b128 v[200:203], v138 offset:59936
	s_waitcnt lgkmcnt(4)
	v_mfma_f32_32x32x16_bf16 v[50:65], v[180:183], v[184:187], v[50:65]
	s_waitcnt lgkmcnt(1)
	v_mfma_f32_32x32x16_bf16 v[34:49], v[196:199], v[184:187], v[34:49]
	ds_read_b128 v[184:187], v133 offset:59904
	ds_read_b128 v[140:143], v133 offset:59936
	s_waitcnt lgkmcnt(1)
	v_mfma_f32_32x32x16_bf16 v[18:33], v[180:183], v[184:187], v[18:33]
	v_mfma_f32_32x32x16_bf16 v[2:17], v[196:199], v[184:187], v[2:17]
	v_mfma_f32_32x32x16_bf16 v[50:65], v[192:195], v[188:191], v[50:65]
	v_mfma_f32_32x32x16_bf16 v[34:49], v[200:203], v[188:191], v[34:49]
	ds_read_b128 v[180:183], v138 offset:55360
	ds_read_b128 v[184:187], v133 offset:55360
	ds_read_b128 v[188:191], v133 offset:55392
	ds_read_b128 v[196:199], v138 offset:55392
	s_waitcnt lgkmcnt(4)
	v_mfma_f32_32x32x16_bf16 v[18:33], v[192:195], v[140:143], v[18:33]
	v_mfma_f32_32x32x16_bf16 v[2:17], v[200:203], v[140:143], v[2:17]
	ds_read_b128 v[192:195], v138 offset:59968
	ds_read_b128 v[140:143], v138 offset:60000
	ds_read_b128 v[208:211], v133 offset:59968
	ds_read_b128 v[144:147], v133 offset:60000
	s_waitcnt vmcnt(11)
	ds_write_b128 v128, v[90:93]
	s_waitcnt vmcnt(10)
	ds_write_b128 v129, v[94:97]
	s_waitcnt vmcnt(9)
	ds_write_b128 v128, v[98:101] offset:18432
	s_waitcnt vmcnt(8)
	ds_write_b128 v129, v[102:105] offset:18432
	s_waitcnt vmcnt(7)
	ds_write_b128 v130, v[106:109] offset:18432
	s_waitcnt vmcnt(6)
	ds_write_b128 v131, v[110:113] offset:18432
	s_waitcnt lgkmcnt(12)
	v_mfma_f32_32x32x16_bf16 v[50:65], v[180:183], v[184:187], v[50:65]
	s_waitcnt lgkmcnt(9)
	v_mfma_f32_32x32x16_bf16 v[34:49], v[192:195], v[184:187], v[34:49]
	s_waitcnt lgkmcnt(7)
	v_mfma_f32_32x32x16_bf16 v[18:33], v[180:183], v[208:211], v[18:33]
	v_mfma_f32_32x32x16_bf16 v[2:17], v[192:195], v[208:211], v[2:17]
	v_mfma_f32_32x32x16_bf16 v[50:65], v[196:199], v[188:191], v[50:65]
	v_mfma_f32_32x32x16_bf16 v[34:49], v[140:143], v[188:191], v[34:49]
	s_waitcnt lgkmcnt(6)
	v_mfma_f32_32x32x16_bf16 v[18:33], v[196:199], v[144:147], v[18:33]
	v_mfma_f32_32x32x16_bf16 v[2:17], v[140:143], v[144:147], v[2:17]
	s_branch .LBB0_1755
